# speedup vs baseline: 1.0012x; 1.0012x over previous
; #define PIN(i) ((const float*)pget(p, (i)))
; __device__ __forceinline__ void phase_prep(const Params& p, int l, unsigned char* lds_g, int part, int c, int G) {
;     ...
;     if (part == 0) {
;         const size_t gt = (size_t)c * NTH + tid, nt = (size_t)G * NTH;
;         bf16_t* CK = (bf16_t*)(ws + WS_CKVS); bf16_t* KP = (bf16_t*)(ws + WS_KPES);
;         const float* cc = PIN(I_CCKV) + (size_t)l * 8 * 2048 * 512; const float* ck = PIN(I_CKPE) + (size_t)l * 8 * 2048 * 64;
;         for (size_t i = gt; i < (size_t)8 * 2048 * 512 / 8; i += nt) { const size_t e = i * 8; const int b = (int)(e / (2048 * 512)); const size_t rem = e - (size_t)b * 2048 * 512;
;             const f32x4 a = *(const f32x4*)(cc + e), d = *(const f32x4*)(cc + e + 4);
.LBB0_404:
	s_or_b64 exec, exec, s[12:13]
	s_mov_b32 s14, 2
	s_mov_b32 s4, 3
	s_ashr_i32 s5, s4, 31
	s_lshl_b64 s[4:5], s[4:5], 3
	s_add_u32 s4, s0, s4
	s_addc_u32 s5, s1, s5
	s_load_dwordx2 s[10:11], s[4:5], 0x0
	v_readlane_b32 s4, v249, 36
	v_ashrrev_i32_e32 v19, 31, v18
	v_readlane_b32 s5, v249, 37
	s_waitcnt vmcnt(0)
	v_lshlrev_b64 v[4:5], 5, v[18:19]
	v_lshl_add_u64 v[2:3], s[4:5], 0, v[18:19]
	s_mov_b64 s[4:5], 0x100000
	v_cmp_gt_u64_e32 vcc, s[4:5], v[2:3]
	s_and_saveexec_b64 s[12:13], vcc
	s_cbranch_execz .LBB0_407
	s_ashr_i32 s15, s14, 31
	s_lshl_b64 s[4:5], s[14:15], 3
	s_add_u32 s4, s0, s4
	s_addc_u32 s5, s1, s5
	s_load_dwordx2 s[4:5], s[4:5], 0x0
	v_readlane_b32 s16, v246, 35
	v_readlane_b32 s17, v246, 36
	s_lshl_b64 s[16:17], s[16:17], 25
	v_readlane_b32 s18, v247, 18
	v_readlane_b32 s19, v247, 19
	s_waitcnt lgkmcnt(0)
	s_add_u32 s4, s4, s18
	s_addc_u32 s5, s5, s19
	s_add_u32 s4, s4, s16
	s_addc_u32 s5, s5, s17
	v_lshl_add_u64 v[6:7], s[4:5], 0, v[4:5]
	v_readlane_b32 s4, v247, 27
	s_add_u32 s4, s6, s4
	v_readlane_b32 s5, v247, 28
	s_addc_u32 s5, s7, s5
	s_mov_b64 s[14:15], 0
	v_lshl_add_u64 v[8:9], v[18:19], 4, s[4:5]
	v_mov_b64_e32 v[10:11], v[2:3]
	s_cmpk_eq_u32 s74, 0x100
	s_cbranch_scc0 .LBB0_406
; __device__ __forceinline__ unsigned cvt_pk(float lo, float hi) { unsigned r; asm volatile("v_cvt_pk_bf16_f32 %0, %1, %2" : "=v"(r) : "v"(lo), "v"(hi)); return r; }
; __device__ __forceinline__ void phase_prep(const Params& p, int l, unsigned char* lds_g, int part, int c, int G) {
;     ...
;         for (size_t i = gt; i < (size_t)8 * 2048 * 512 / 8; i += nt) { const size_t e = i * 8; const int b = (int)(e / (2048 * 512)); const size_t rem = e - (size_t)b * 2048 * 512;
;             const f32x4 a = *(const f32x4*)(cc + e), d = *(const f32x4*)(cc + e + 4);
;             u32x4 w; w.x = cvt_pk(a[0], a[1]); w.y = cvt_pk(a[2], a[3]); w.z = cvt_pk(d[0], d[1]); w.w = cvt_pk(d[2], d[3]);
;             *(u32x4*)(CK + (size_t)b * SKV * 512 + rem) = w; }
	global_load_dwordx4 v[32:35], v[6:7], off offset:-16
	global_load_dwordx4 v[36:39], v[6:7], off
	v_alignbit_b32 v0, v11, v10, 17
	v_lshlrev_b32_e32 v24, 4, v11
	s_mov_b32 s4, 0xffe00000
	v_mad_u64_u32 v[96:97], s[4:5], v0, s4, v[8:9]
	v_and_b32_e32 v24, 0xffe00000, v24
	v_lshl_add_u64 v[10:11], v[10:11], 0, s[82:83]
	v_sub_u32_e32 v97, v97, v24
	v_sub_u32_e32 v97, v97, v0
	s_mov_b32 s4, 0x204000
	v_lshl_add_u64 v[6:7], v[6:7], 0, s[46:47]
	v_lshl_add_u64 v[8:9], v[8:9], 0, s[90:91]
	v_mad_u64_u32 v[96:97], s[4:5], v0, s4, v[96:97]
	global_load_dwordx4 v[40:43], v[6:7], off offset:-16
	global_load_dwordx4 v[44:47], v[6:7], off
	v_alignbit_b32 v0, v11, v10, 17
	v_lshlrev_b32_e32 v24, 4, v11
	s_mov_b32 s4, 0xffe00000
	v_mad_u64_u32 v[98:99], s[4:5], v0, s4, v[8:9]
	v_and_b32_e32 v24, 0xffe00000, v24
	v_lshl_add_u64 v[10:11], v[10:11], 0, s[82:83]
	v_sub_u32_e32 v99, v99, v24
	v_sub_u32_e32 v99, v99, v0
	s_mov_b32 s4, 0x204000
	v_lshl_add_u64 v[6:7], v[6:7], 0, s[46:47]
	v_lshl_add_u64 v[8:9], v[8:9], 0, s[90:91]
	v_mad_u64_u32 v[98:99], s[4:5], v0, s4, v[98:99]
	global_load_dwordx4 v[48:51], v[6:7], off offset:-16
	global_load_dwordx4 v[52:55], v[6:7], off
	v_alignbit_b32 v0, v11, v10, 17
	v_lshlrev_b32_e32 v24, 4, v11
	s_mov_b32 s4, 0xffe00000
	v_mad_u64_u32 v[100:101], s[4:5], v0, s4, v[8:9]
	v_and_b32_e32 v24, 0xffe00000, v24
	v_lshl_add_u64 v[10:11], v[10:11], 0, s[82:83]
	v_sub_u32_e32 v101, v101, v24
	v_sub_u32_e32 v101, v101, v0
	s_mov_b32 s4, 0x204000
	v_lshl_add_u64 v[6:7], v[6:7], 0, s[46:47]
	v_lshl_add_u64 v[8:9], v[8:9], 0, s[90:91]
	v_mad_u64_u32 v[100:101], s[4:5], v0, s4, v[100:101]
	global_load_dwordx4 v[56:59], v[6:7], off offset:-16
	global_load_dwordx4 v[60:63], v[6:7], off
	v_alignbit_b32 v0, v11, v10, 17
	v_lshlrev_b32_e32 v24, 4, v11
	s_mov_b32 s4, 0xffe00000
	v_mad_u64_u32 v[102:103], s[4:5], v0, s4, v[8:9]
	v_and_b32_e32 v24, 0xffe00000, v24
	v_lshl_add_u64 v[10:11], v[10:11], 0, s[82:83]
	v_sub_u32_e32 v103, v103, v24
	v_sub_u32_e32 v103, v103, v0
	s_mov_b32 s4, 0x204000
	v_lshl_add_u64 v[6:7], v[6:7], 0, s[46:47]
	v_lshl_add_u64 v[8:9], v[8:9], 0, s[90:91]
	v_mad_u64_u32 v[102:103], s[4:5], v0, s4, v[102:103]
	global_load_dwordx4 v[64:67], v[6:7], off offset:-16
	global_load_dwordx4 v[68:71], v[6:7], off
	v_alignbit_b32 v0, v11, v10, 17
	v_lshlrev_b32_e32 v24, 4, v11
	s_mov_b32 s4, 0xffe00000
	v_mad_u64_u32 v[104:105], s[4:5], v0, s4, v[8:9]
	v_and_b32_e32 v24, 0xffe00000, v24
	v_lshl_add_u64 v[10:11], v[10:11], 0, s[82:83]
	v_sub_u32_e32 v105, v105, v24
	v_sub_u32_e32 v105, v105, v0
	s_mov_b32 s4, 0x204000
	v_lshl_add_u64 v[6:7], v[6:7], 0, s[46:47]
	v_lshl_add_u64 v[8:9], v[8:9], 0, s[90:91]
	v_mad_u64_u32 v[104:105], s[4:5], v0, s4, v[104:105]
	global_load_dwordx4 v[72:75], v[6:7], off offset:-16
	global_load_dwordx4 v[76:79], v[6:7], off
	v_alignbit_b32 v0, v11, v10, 17
	v_lshlrev_b32_e32 v24, 4, v11
	s_mov_b32 s4, 0xffe00000
	v_mad_u64_u32 v[106:107], s[4:5], v0, s4, v[8:9]
	v_and_b32_e32 v24, 0xffe00000, v24
	v_lshl_add_u64 v[10:11], v[10:11], 0, s[82:83]
	v_sub_u32_e32 v107, v107, v24
	v_sub_u32_e32 v107, v107, v0
	s_mov_b32 s4, 0x204000
	v_lshl_add_u64 v[6:7], v[6:7], 0, s[46:47]
	v_lshl_add_u64 v[8:9], v[8:9], 0, s[90:91]
	v_mad_u64_u32 v[106:107], s[4:5], v0, s4, v[106:107]
	global_load_dwordx4 v[80:83], v[6:7], off offset:-16
	global_load_dwordx4 v[84:87], v[6:7], off
	v_alignbit_b32 v0, v11, v10, 17
	v_lshlrev_b32_e32 v24, 4, v11
	s_mov_b32 s4, 0xffe00000
	v_mad_u64_u32 v[108:109], s[4:5], v0, s4, v[8:9]
	v_and_b32_e32 v24, 0xffe00000, v24
	v_lshl_add_u64 v[10:11], v[10:11], 0, s[82:83]
	v_sub_u32_e32 v109, v109, v24
	v_sub_u32_e32 v109, v109, v0
	s_mov_b32 s4, 0x204000
	v_lshl_add_u64 v[6:7], v[6:7], 0, s[46:47]
	v_lshl_add_u64 v[8:9], v[8:9], 0, s[90:91]
	v_mad_u64_u32 v[108:109], s[4:5], v0, s4, v[108:109]
	global_load_dwordx4 v[88:91], v[6:7], off offset:-16
	global_load_dwordx4 v[92:95], v[6:7], off
	v_alignbit_b32 v0, v11, v10, 17
	v_lshlrev_b32_e32 v24, 4, v11
	s_mov_b32 s4, 0xffe00000
	v_mad_u64_u32 v[110:111], s[4:5], v0, s4, v[8:9]
	v_and_b32_e32 v24, 0xffe00000, v24
	v_lshl_add_u64 v[10:11], v[10:11], 0, s[82:83]
	v_sub_u32_e32 v111, v111, v24
	v_sub_u32_e32 v111, v111, v0
	s_mov_b32 s4, 0x204000
	v_lshl_add_u64 v[6:7], v[6:7], 0, s[46:47]
	v_lshl_add_u64 v[8:9], v[8:9], 0, s[90:91]
	v_mad_u64_u32 v[110:111], s[4:5], v0, s4, v[110:111]
	s_waitcnt vmcnt(15)
	v_cvt_pk_bf16_f32 v32, v32, v33
	v_cvt_pk_bf16_f32 v33, v34, v35
	s_waitcnt vmcnt(14)
	v_cvt_pk_bf16_f32 v34, v36, v37
	v_cvt_pk_bf16_f32 v35, v38, v39
	global_store_dwordx4 v[96:97], v[32:35], off
	s_waitcnt vmcnt(14)
	v_cvt_pk_bf16_f32 v40, v40, v41
	v_cvt_pk_bf16_f32 v41, v42, v43
	s_waitcnt vmcnt(13)
	v_cvt_pk_bf16_f32 v42, v44, v45
	v_cvt_pk_bf16_f32 v43, v46, v47
	global_store_dwordx4 v[98:99], v[40:43], off
	s_waitcnt vmcnt(13)
	v_cvt_pk_bf16_f32 v48, v48, v49
	v_cvt_pk_bf16_f32 v49, v50, v51
	s_waitcnt vmcnt(12)
	v_cvt_pk_bf16_f32 v50, v52, v53
	v_cvt_pk_bf16_f32 v51, v54, v55
	global_store_dwordx4 v[100:101], v[48:51], off
	s_waitcnt vmcnt(12)
	v_cvt_pk_bf16_f32 v56, v56, v57
	v_cvt_pk_bf16_f32 v57, v58, v59
	s_waitcnt vmcnt(11)
	v_cvt_pk_bf16_f32 v58, v60, v61
	v_cvt_pk_bf16_f32 v59, v62, v63
	global_store_dwordx4 v[102:103], v[56:59], off
	s_waitcnt vmcnt(11)
	v_cvt_pk_bf16_f32 v64, v64, v65
	v_cvt_pk_bf16_f32 v65, v66, v67
	s_waitcnt vmcnt(10)
	v_cvt_pk_bf16_f32 v66, v68, v69
	v_cvt_pk_bf16_f32 v67, v70, v71
	global_store_dwordx4 v[104:105], v[64:67], off
	s_waitcnt vmcnt(10)
	v_cvt_pk_bf16_f32 v72, v72, v73
	v_cvt_pk_bf16_f32 v73, v74, v75
	s_waitcnt vmcnt(9)
	v_cvt_pk_bf16_f32 v74, v76, v77
	v_cvt_pk_bf16_f32 v75, v78, v79
	global_store_dwordx4 v[106:107], v[72:75], off
	s_waitcnt vmcnt(9)
	v_cvt_pk_bf16_f32 v80, v80, v81
	v_cvt_pk_bf16_f32 v81, v82, v83
	s_waitcnt vmcnt(8)
	v_cvt_pk_bf16_f32 v82, v84, v85
	v_cvt_pk_bf16_f32 v83, v86, v87
	global_store_dwordx4 v[108:109], v[80:83], off
	s_waitcnt vmcnt(8)
	v_cvt_pk_bf16_f32 v88, v88, v89
	v_cvt_pk_bf16_f32 v89, v90, v91
	s_waitcnt vmcnt(7)
	v_cvt_pk_bf16_f32 v90, v92, v93
	v_cvt_pk_bf16_f32 v91, v94, v95
	global_store_dwordx4 v[110:111], v[88:91], off
	s_branch .LBB0_407
